# GEMM K-loops 1 and 3: staging LDS-DMA loads use scalar base + 32-bit VGPR offset (no 64-bit VALU address adds in the load segments)
# baseline (speedup 1.0000x reference)
; #define PG8_STAGE(bufoff, gbase, voff) do { _Pragma("unroll") for (int _i = 0; _i < 2; ++_i) \
;         __builtin_amdgcn_global_load_lds((const unsigned*)((const char*)(gbase) + (voff)[_i]), (PG8_LAS unsigned*)(lds + (bufoff) + ldsw + _i * 8192), 16, 0, 0); } while (0)
; #define PG8_LDA(dst, b, h) do { _Pragma("unroll") for (int m = 0; m < 4; ++m) _Pragma("unroll") for (int k = 0; k < 2; ++k) dst[m][k] = *(const PG8_LAS bf16x8*)(lds + PG8_SA(b, h) + aoff + m * 2048 + k * 1024); } while (0)
; #define PG8_LDB(dst, b, h) do { _Pragma("unroll") for (int n = 0; n < 2; ++n) _Pragma("unroll") for (int k = 0; k < 2; ++k) dst[n][k] = *(const PG8_LAS bf16x8*)(lds + PG8_SB(b, h) + boff + n * 2048 + k * 1024); } while (0)
; #define PG8_MMA(ai, bj, At, Bt) do { __builtin_amdgcn_s_setprio(1); _Pragma("unroll") for (int m = 0; m < 4; ++m) _Pragma("unroll") for (int n = 0; n < 2; ++n) _Pragma("unroll") for (int k = 0; k < 2; ++k) \
;         acc[ai][bj][m][n] = __builtin_amdgcn_mfma_f32_16x16x32_bf16(Bt[n][k], At[m][k], acc[ai][bj][m][n], 0, 0, 0); __builtin_amdgcn_s_setprio(0); } while (0)
; #define PG8_WAIT_V(n) asm volatile("s_waitcnt vmcnt(" #n ")" ::: "memory")
; #define PG8_WAIT_L(n) asm volatile("s_waitcnt lgkmcnt(" #n ")" ::: "memory")
; #define PG8_BAR __builtin_amdgcn_s_barrier()
; #define PG8_SCHED __builtin_amdgcn_sched_barrier(0)
; template <class Epi, class Sched, bool ALIGN_EPI = false, bool SP2 = false>
; __device__ __forceinline__ void gemm_phase(PG8_LAS unsigned char* lds, const Gemm g, const Sched& S, const Epi& E) {
;     ...
;             PG8_LDB(B0, 0, 0); PG8_LDB(B1, 0, 1); PG8_SCHED; PG8_LDA(At, 0, 0); PG8_STAGE(PG8_SA(1, 1), a1 + hstep, voffA);
;             PG8_WAIT_V(8); PG8_WAIT_L(0); PG8_BAR; PG8_MMA(0, 0, At, B0); PG8_MMA(0, 1, At, B1); PG8_BAR; PG8_SCHED;
;             PG8_LDA(At, 0, 1); PG8_STAGE(PG8_SB(0, 0), b2, voffB); PG8_STAGE(PG8_SB(0, 1), b2 + hstep, voffB); PG8_STAGE(PG8_SA(0, 0), a2, voffA);
;             PG8_WAIT_V(8); PG8_WAIT_L(0); PG8_BAR; PG8_MMA(1, 0, At, B0); PG8_MMA(1, 1, At, B1); PG8_BAR; PG8_SCHED;
.LBB0_165:
	s_add_u32 s16, s8, 0xfffc0080
	s_addc_u32 s17, s9, -1
	s_add_i32 s18, 0, 0x10000
	s_cmp_eq_u32 s55, 12
	s_cselect_b32 s43, s14, s17
	s_cselect_b32 s42, s15, s16
	v_add_u32_e32 v0, s18, v194
	s_cselect_b32 s41, s13, s54
	s_cselect_b32 s40, s25, s53
	s_add_i32 s19, 0, 0x14000
	ds_read_b128 v[136:139], v0
	ds_read_b128 v[140:143], v0 offset:1024
	ds_read_b128 v[144:147], v0 offset:2048
	ds_read_b128 v[148:151], v0 offset:3072
	v_add_u32_e32 v0, s19, v194
	ds_read_b128 v[152:155], v0
	ds_read_b128 v[186:189], v0 offset:1024
	ds_read_b128 v[190:193], v0 offset:2048
	ds_read_b128 v[198:201], v0 offset:3072
	s_add_i32 m0, s45, 0xc000
	ds_read_b128 v[210:213], v196
	ds_read_b128 v[214:217], v196 offset:1024
	ds_read_b128 v[218:221], v196 offset:2048
	ds_read_b128 v[222:225], v196 offset:3072
	ds_read_b128 v[226:229], v196 offset:4096
	ds_read_b128 v[230:233], v196 offset:5120
	ds_read_b128 v[234:237], v196 offset:6144
	ds_read_b128 v[238:241], v196 offset:7168
	global_load_lds_dwordx4 v182, s[8:9]
	s_add_i32 m0, s45, 0xe000
	s_nop 0
	global_load_lds_dwordx4 v184, s[8:9]
	s_waitcnt vmcnt(8)
	s_waitcnt lgkmcnt(0)
	s_barrier
	s_waitcnt lgkmcnt(0)
	v_mfma_f32_16x16x32_bf16 v[132:135], v[136:139], v[210:213], v[132:135]
	v_mfma_f32_16x16x32_bf16 v[128:131], v[144:147], v[210:213], v[128:131]
	v_mfma_f32_16x16x32_bf16 v[124:127], v[136:139], v[218:221], v[124:127]
	v_mfma_f32_16x16x32_bf16 v[120:123], v[144:147], v[218:221], v[120:123]
	s_setprio 1
	v_mfma_f32_16x16x32_bf16 v[116:119], v[136:139], v[226:229], v[116:119]
	v_mfma_f32_16x16x32_bf16 v[112:115], v[144:147], v[226:229], v[112:115]
	v_mfma_f32_16x16x32_bf16 v[108:111], v[136:139], v[234:237], v[108:111]
	v_mfma_f32_16x16x32_bf16 v[104:107], v[144:147], v[234:237], v[104:107]
	v_mfma_f32_16x16x32_bf16 v[132:135], v[140:143], v[214:217], v[132:135]
	v_mfma_f32_16x16x32_bf16 v[128:131], v[148:151], v[214:217], v[128:131]
	v_mfma_f32_16x16x32_bf16 v[124:127], v[140:143], v[222:225], v[124:127]
	v_mfma_f32_16x16x32_bf16 v[120:123], v[148:151], v[222:225], v[120:123]
	v_mfma_f32_16x16x32_bf16 v[116:119], v[140:143], v[230:233], v[116:119]
	v_mfma_f32_16x16x32_bf16 v[112:115], v[148:151], v[230:233], v[112:115]
	v_mfma_f32_16x16x32_bf16 v[108:111], v[140:143], v[238:241], v[108:111]
	v_mfma_f32_16x16x32_bf16 v[104:107], v[148:151], v[238:241], v[104:107]
	s_setprio 0
	s_setprio 1
	v_mfma_f32_16x16x32_bf16 v[84:87], v[152:155], v[210:213], v[84:87]
	v_mfma_f32_16x16x32_bf16 v[76:79], v[190:193], v[210:213], v[76:79]
	v_mfma_f32_16x16x32_bf16 v[68:71], v[152:155], v[218:221], v[68:71]
	v_mfma_f32_16x16x32_bf16 v[64:67], v[190:193], v[218:221], v[64:67]
	v_mfma_f32_16x16x32_bf16 v[52:55], v[152:155], v[226:229], v[52:55]
	v_mfma_f32_16x16x32_bf16 v[48:51], v[190:193], v[226:229], v[48:51]
	v_mfma_f32_16x16x32_bf16 v[44:47], v[152:155], v[234:237], v[44:47]
	v_mfma_f32_16x16x32_bf16 v[40:43], v[190:193], v[234:237], v[40:43]
	v_mfma_f32_16x16x32_bf16 v[84:87], v[186:189], v[214:217], v[84:87]
	v_mfma_f32_16x16x32_bf16 v[76:79], v[198:201], v[214:217], v[76:79]
	v_mfma_f32_16x16x32_bf16 v[68:71], v[186:189], v[222:225], v[68:71]
	v_mfma_f32_16x16x32_bf16 v[64:67], v[198:201], v[222:225], v[64:67]
	s_barrier
	v_mfma_f32_16x16x32_bf16 v[52:55], v[186:189], v[230:233], v[52:55]
	v_mfma_f32_16x16x32_bf16 v[48:51], v[198:201], v[230:233], v[48:51]
	v_mfma_f32_16x16x32_bf16 v[44:47], v[186:189], v[238:241], v[44:47]
	v_mfma_f32_16x16x32_bf16 v[40:43], v[198:201], v[238:241], v[40:43]
	s_setprio 0
	s_add_i32 s16, s18, s44
	s_mov_b32 m0, s16
	ds_read_b128 v[210:213], v196 offset:16384
	ds_read_b128 v[214:217], v196 offset:17408
	ds_read_b128 v[218:221], v196 offset:18432
	ds_read_b128 v[222:225], v196 offset:19456
	ds_read_b128 v[226:229], v196 offset:20480
	ds_read_b128 v[230:233], v196 offset:21504
	ds_read_b128 v[234:237], v196 offset:22528
	ds_read_b128 v[238:241], v196 offset:23552
	global_load_lds_dwordx4 v162, s[40:41]
	s_add_i32 m0, s16, 0x2000
	s_add_u32 s16, s40, 0x40000
	s_addc_u32 s17, s41, 0
	s_add_i32 s18, s19, s44
	global_load_lds_dwordx4 v158, s[40:41]
	s_mov_b32 m0, s18
	s_nop 0
	global_load_lds_dwordx4 v162, s[16:17]
	s_add_i32 m0, s18, 0x2000
	s_nop 0
	global_load_lds_dwordx4 v158, s[16:17]
	s_mov_b32 m0, s45
	s_nop 0
	global_load_lds_dwordx4 v178, s[42:43]
	s_mov_b32 m0, s46
	s_nop 0
	global_load_lds_dwordx4 v160, s[42:43]
	s_waitcnt vmcnt(8)
	s_waitcnt lgkmcnt(0)
	s_barrier
	s_waitcnt lgkmcnt(0)
	v_mfma_f32_16x16x32_bf16 v[100:103], v[136:139], v[210:213], v[100:103]
	v_mfma_f32_16x16x32_bf16 v[96:99], v[144:147], v[210:213], v[96:99]
	v_mfma_f32_16x16x32_bf16 v[92:95], v[136:139], v[218:221], v[92:95]
	v_mfma_f32_16x16x32_bf16 v[88:91], v[144:147], v[218:221], v[88:91]
	s_setprio 1
	v_mfma_f32_16x16x32_bf16 v[80:83], v[136:139], v[226:229], v[80:83]
	v_mfma_f32_16x16x32_bf16 v[72:75], v[144:147], v[226:229], v[72:75]
	v_mfma_f32_16x16x32_bf16 v[60:63], v[136:139], v[234:237], v[60:63]
	v_mfma_f32_16x16x32_bf16 v[56:59], v[144:147], v[234:237], v[56:59]
	v_mfma_f32_16x16x32_bf16 v[100:103], v[140:143], v[214:217], v[100:103]
	v_mfma_f32_16x16x32_bf16 v[96:99], v[148:151], v[214:217], v[96:99]
	v_mfma_f32_16x16x32_bf16 v[92:95], v[140:143], v[222:225], v[92:95]
	v_mfma_f32_16x16x32_bf16 v[88:91], v[148:151], v[222:225], v[88:91]
	v_mfma_f32_16x16x32_bf16 v[80:83], v[140:143], v[230:233], v[80:83]
	v_mfma_f32_16x16x32_bf16 v[72:75], v[148:151], v[230:233], v[72:75]
	v_mfma_f32_16x16x32_bf16 v[60:63], v[140:143], v[238:241], v[60:63]
	v_mfma_f32_16x16x32_bf16 v[56:59], v[148:151], v[238:241], v[56:59]
	s_setprio 0
	s_setprio 1
	v_mfma_f32_16x16x32_bf16 v[36:39], v[152:155], v[210:213], v[36:39]
	v_mfma_f32_16x16x32_bf16 v[32:35], v[190:193], v[210:213], v[32:35]
	v_mfma_f32_16x16x32_bf16 v[28:31], v[152:155], v[218:221], v[28:31]
	v_mfma_f32_16x16x32_bf16 v[24:27], v[190:193], v[218:221], v[24:27]
	v_mfma_f32_16x16x32_bf16 v[20:23], v[152:155], v[226:229], v[20:23]
	v_mfma_f32_16x16x32_bf16 v[16:19], v[190:193], v[226:229], v[16:19]
	v_mfma_f32_16x16x32_bf16 v[12:15], v[152:155], v[234:237], v[12:15]
	v_mfma_f32_16x16x32_bf16 v[8:11], v[190:193], v[234:237], v[8:11]
	v_mfma_f32_16x16x32_bf16 v[36:39], v[186:189], v[214:217], v[36:39]
	v_mfma_f32_16x16x32_bf16 v[32:35], v[198:201], v[214:217], v[32:35]
	v_mfma_f32_16x16x32_bf16 v[28:31], v[186:189], v[222:225], v[28:31]
	v_mfma_f32_16x16x32_bf16 v[24:27], v[198:201], v[222:225], v[24:27]
	s_barrier
; #define PG8_STAGE(bufoff, gbase, voff) do { _Pragma("unroll") for (int _i = 0; _i < 2; ++_i) \
;         __builtin_amdgcn_global_load_lds((const unsigned*)((const char*)(gbase) + (voff)[_i]), (PG8_LAS unsigned*)(lds + (bufoff) + ldsw + _i * 8192), 16, 0, 0); } while (0)
; #define PG8_LDA(dst, b, h) do { _Pragma("unroll") for (int m = 0; m < 4; ++m) _Pragma("unroll") for (int k = 0; k < 2; ++k) dst[m][k] = *(const PG8_LAS bf16x8*)(lds + PG8_SA(b, h) + aoff + m * 2048 + k * 1024); } while (0)
; #define PG8_LDB(dst, b, h) do { _Pragma("unroll") for (int n = 0; n < 2; ++n) _Pragma("unroll") for (int k = 0; k < 2; ++k) dst[n][k] = *(const PG8_LAS bf16x8*)(lds + PG8_SB(b, h) + boff + n * 2048 + k * 1024); } while (0)
; #define PG8_MMA(ai, bj, At, Bt) do { __builtin_amdgcn_s_setprio(1); _Pragma("unroll") for (int m = 0; m < 4; ++m) _Pragma("unroll") for (int n = 0; n < 2; ++n) _Pragma("unroll") for (int k = 0; k < 2; ++k) \
;         acc[ai][bj][m][n] = __builtin_amdgcn_mfma_f32_16x16x32_bf16(Bt[n][k], At[m][k], acc[ai][bj][m][n], 0, 0, 0); __builtin_amdgcn_s_setprio(0); } while (0)
; #define PG8_WAIT_V(n) asm volatile("s_waitcnt vmcnt(" #n ")" ::: "memory")
; #define PG8_WAIT_L(n) asm volatile("s_waitcnt lgkmcnt(" #n ")" ::: "memory")
; #define PG8_BAR __builtin_amdgcn_s_barrier()
; #define PG8_SCHED __builtin_amdgcn_sched_barrier(0)
; template <class Epi, class Sched, bool ALIGN_EPI = false, bool SP2 = false>
; __device__ __forceinline__ void gemm_phase(PG8_LAS unsigned char* lds, const Gemm g, const Sched& S, const Epi& E) {
;     ...
;             PG8_LDB(B0, 1, 0); PG8_LDB(B1, 1, 1); PG8_SCHED; PG8_LDA(At, 1, 0); PG8_STAGE(PG8_SA(0, 1), a2 + hstep, voffA);
;             PG8_WAIT_V(8); PG8_WAIT_L(0); PG8_BAR; PG8_MMA(0, 0, At, B0); PG8_MMA(0, 1, At, B1); PG8_BAR; PG8_SCHED;
	v_mfma_f32_16x16x32_bf16 v[20:23], v[186:189], v[230:233], v[20:23]
	v_mfma_f32_16x16x32_bf16 v[16:19], v[198:201], v[230:233], v[16:19]
	v_mfma_f32_16x16x32_bf16 v[12:15], v[186:189], v[238:241], v[12:15]
	v_mfma_f32_16x16x32_bf16 v[8:11], v[198:201], v[238:241], v[8:11]
	s_setprio 0
	s_add_i32 s18, 0, 0x18000
	v_add_u32_e32 v0, s18, v194
	ds_read_b128 v[136:139], v0
	ds_read_b128 v[140:143], v0 offset:1024
	ds_read_b128 v[144:147], v0 offset:2048
	ds_read_b128 v[148:151], v0 offset:3072
	v_add_u32_e32 v0, s33, v194
	ds_read_b128 v[152:155], v0
	ds_read_b128 v[186:189], v0 offset:1024
	ds_read_b128 v[190:193], v0 offset:2048
	ds_read_b128 v[198:201], v0 offset:3072
	s_add_u32 s16, s42, 0x40000
	s_addc_u32 s17, s43, 0
	s_mov_b32 m0, s47
	ds_read_b128 v[210:213], v196 offset:32768
	ds_read_b128 v[214:217], v196 offset:33792
	ds_read_b128 v[218:221], v196 offset:34816
	ds_read_b128 v[222:225], v196 offset:35840
	ds_read_b128 v[226:229], v196 offset:36864
	ds_read_b128 v[230:233], v196 offset:37888
	ds_read_b128 v[234:237], v196 offset:38912
	ds_read_b128 v[238:241], v196 offset:39936
	global_load_lds_dwordx4 v178, s[16:17]
	s_mov_b32 m0, s48
	s_nop 0
	global_load_lds_dwordx4 v160, s[16:17]
	s_waitcnt vmcnt(8)
	s_waitcnt lgkmcnt(0)
	s_barrier
	s_waitcnt lgkmcnt(0)
	v_mfma_f32_16x16x32_bf16 v[132:135], v[136:139], v[210:213], v[132:135]
	v_mfma_f32_16x16x32_bf16 v[128:131], v[144:147], v[210:213], v[128:131]
	v_mfma_f32_16x16x32_bf16 v[124:127], v[136:139], v[218:221], v[124:127]
	v_mfma_f32_16x16x32_bf16 v[120:123], v[144:147], v[218:221], v[120:123]
	s_setprio 1
	v_mfma_f32_16x16x32_bf16 v[116:119], v[136:139], v[226:229], v[116:119]
	v_mfma_f32_16x16x32_bf16 v[112:115], v[144:147], v[226:229], v[112:115]
	v_mfma_f32_16x16x32_bf16 v[108:111], v[136:139], v[234:237], v[108:111]
	v_mfma_f32_16x16x32_bf16 v[104:107], v[144:147], v[234:237], v[104:107]
	v_mfma_f32_16x16x32_bf16 v[132:135], v[140:143], v[214:217], v[132:135]
	v_mfma_f32_16x16x32_bf16 v[128:131], v[148:151], v[214:217], v[128:131]
	v_mfma_f32_16x16x32_bf16 v[124:127], v[140:143], v[222:225], v[124:127]
	v_mfma_f32_16x16x32_bf16 v[120:123], v[148:151], v[222:225], v[120:123]
	v_mfma_f32_16x16x32_bf16 v[116:119], v[140:143], v[230:233], v[116:119]
	v_mfma_f32_16x16x32_bf16 v[112:115], v[148:151], v[230:233], v[112:115]
	v_mfma_f32_16x16x32_bf16 v[108:111], v[140:143], v[238:241], v[108:111]
	v_mfma_f32_16x16x32_bf16 v[104:107], v[148:151], v[238:241], v[104:107]
	s_setprio 0
	s_setprio 1
	v_mfma_f32_16x16x32_bf16 v[84:87], v[152:155], v[210:213], v[84:87]
	v_mfma_f32_16x16x32_bf16 v[76:79], v[190:193], v[210:213], v[76:79]
	v_mfma_f32_16x16x32_bf16 v[68:71], v[152:155], v[218:221], v[68:71]
	v_mfma_f32_16x16x32_bf16 v[64:67], v[190:193], v[218:221], v[64:67]
	v_mfma_f32_16x16x32_bf16 v[52:55], v[152:155], v[226:229], v[52:55]
	v_mfma_f32_16x16x32_bf16 v[48:51], v[190:193], v[226:229], v[48:51]
	v_mfma_f32_16x16x32_bf16 v[44:47], v[152:155], v[234:237], v[44:47]
	v_mfma_f32_16x16x32_bf16 v[40:43], v[190:193], v[234:237], v[40:43]
	v_mfma_f32_16x16x32_bf16 v[84:87], v[186:189], v[214:217], v[84:87]
	v_mfma_f32_16x16x32_bf16 v[76:79], v[198:201], v[214:217], v[76:79]
	v_mfma_f32_16x16x32_bf16 v[68:71], v[186:189], v[222:225], v[68:71]
	v_mfma_f32_16x16x32_bf16 v[64:67], v[198:201], v[222:225], v[64:67]
	s_barrier
; #define PG8_STAGE(bufoff, gbase, voff) do { _Pragma("unroll") for (int _i = 0; _i < 2; ++_i) \
;         __builtin_amdgcn_global_load_lds((const unsigned*)((const char*)(gbase) + (voff)[_i]), (PG8_LAS unsigned*)(lds + (bufoff) + ldsw + _i * 8192), 16, 0, 0); } while (0)
; #define PG8_LDA(dst, b, h) do { _Pragma("unroll") for (int m = 0; m < 4; ++m) _Pragma("unroll") for (int k = 0; k < 2; ++k) dst[m][k] = *(const PG8_LAS bf16x8*)(lds + PG8_SA(b, h) + aoff + m * 2048 + k * 1024); } while (0)
; #define PG8_MMA(ai, bj, At, Bt) do { __builtin_amdgcn_s_setprio(1); _Pragma("unroll") for (int m = 0; m < 4; ++m) _Pragma("unroll") for (int n = 0; n < 2; ++n) _Pragma("unroll") for (int k = 0; k < 2; ++k) \
;         acc[ai][bj][m][n] = __builtin_amdgcn_mfma_f32_16x16x32_bf16(Bt[n][k], At[m][k], acc[ai][bj][m][n], 0, 0, 0); __builtin_amdgcn_s_setprio(0); } while (0)
; #define PG8_WAIT_V(n) asm volatile("s_waitcnt vmcnt(" #n ")" ::: "memory")
; #define PG8_WAIT_L(n) asm volatile("s_waitcnt lgkmcnt(" #n ")" ::: "memory")
; #define PG8_BAR __builtin_amdgcn_s_barrier()
; #define PG8_SCHED __builtin_amdgcn_sched_barrier(0)
; template <class Epi, class Sched, bool ALIGN_EPI = false, bool SP2 = false>
; __device__ __forceinline__ void gemm_phase(PG8_LAS unsigned char* lds, const Gemm g, const Sched& S, const Epi& E) {
;     ...
;         for (int t = 0; t < nt; t += 2) {
;             const bool last = (t == nt - 2);
;             const char* a1 = cA + (size_t)(t + 1) * kstep;
;             const char* a2 = last ? nA : cA + (size_t)(t + 2) * kstep; const char* b2 = last ? nB : cB + (size_t)(t + 2) * kstep;
;             const char* a3 = a2 + kstep; const char* b3 = b2 + kstep;
;     ...
;             PG8_LDA(At, 1, 1); PG8_STAGE(PG8_SB(1, 0), b3, voffB); PG8_STAGE(PG8_SB(1, 1), b3 + hstep, voffB); PG8_STAGE(PG8_SA(1, 0), a3, voffA);
;             PG8_WAIT_V(8); PG8_WAIT_L(0); PG8_BAR; PG8_MMA(1, 0, At, B0); PG8_MMA(1, 1, At, B1); PG8_BAR; PG8_SCHED;
	v_mfma_f32_16x16x32_bf16 v[52:55], v[186:189], v[230:233], v[52:55]
	v_mfma_f32_16x16x32_bf16 v[48:51], v[198:201], v[230:233], v[48:51]
	v_mfma_f32_16x16x32_bf16 v[44:47], v[186:189], v[238:241], v[44:47]
	v_mfma_f32_16x16x32_bf16 v[40:43], v[198:201], v[238:241], v[40:43]
	s_setprio 0
	s_add_i32 m0, s18, s44
	s_add_u32 s16, s40, 0x80
	s_addc_u32 s17, s41, 0
	ds_read_b128 v[210:213], v196 offset:49152
	ds_read_b128 v[214:217], v196 offset:50176
	ds_read_b128 v[218:221], v196 offset:51200
	ds_read_b128 v[222:225], v196 offset:52224
	ds_read_b128 v[226:229], v196 offset:53248
	ds_read_b128 v[230:233], v196 offset:54272
	ds_read_b128 v[234:237], v196 offset:55296
	ds_read_b128 v[238:241], v196 offset:56320
	global_load_lds_dwordx4 v162, s[16:17]
	s_add_i32 m0, m0, 0x2000
	s_nop 0
	global_load_lds_dwordx4 v158, s[16:17]
	s_add_u32 s16, s40, 0x40080
	s_addc_u32 s17, s41, 0
	s_add_i32 m0, s33, s44
	s_nop 0
	global_load_lds_dwordx4 v162, s[16:17]
	s_add_i32 m0, m0, 0x2000
	s_nop 0
	global_load_lds_dwordx4 v158, s[16:17]
	s_add_u32 s16, s42, 0x80
	s_addc_u32 s17, s43, 0
	s_mov_b32 m0, s49
	s_nop 0
	global_load_lds_dwordx4 v178, s[16:17]
	s_mov_b32 m0, s50
	s_nop 0
	global_load_lds_dwordx4 v160, s[16:17]
	s_waitcnt vmcnt(8)
	s_waitcnt lgkmcnt(0)
	s_barrier
	s_waitcnt lgkmcnt(0)
	v_mfma_f32_16x16x32_bf16 v[100:103], v[136:139], v[210:213], v[100:103]
	v_mfma_f32_16x16x32_bf16 v[96:99], v[144:147], v[210:213], v[96:99]
	v_mfma_f32_16x16x32_bf16 v[92:95], v[136:139], v[218:221], v[92:95]
	v_mfma_f32_16x16x32_bf16 v[88:91], v[144:147], v[218:221], v[88:91]
	s_setprio 1
	v_mfma_f32_16x16x32_bf16 v[80:83], v[136:139], v[226:229], v[80:83]
	v_mfma_f32_16x16x32_bf16 v[72:75], v[144:147], v[226:229], v[72:75]
	v_mfma_f32_16x16x32_bf16 v[60:63], v[136:139], v[234:237], v[60:63]
	v_mfma_f32_16x16x32_bf16 v[56:59], v[144:147], v[234:237], v[56:59]
	v_mfma_f32_16x16x32_bf16 v[100:103], v[140:143], v[214:217], v[100:103]
	v_mfma_f32_16x16x32_bf16 v[96:99], v[148:151], v[214:217], v[96:99]
	v_mfma_f32_16x16x32_bf16 v[92:95], v[140:143], v[222:225], v[92:95]
	v_mfma_f32_16x16x32_bf16 v[88:91], v[148:151], v[222:225], v[88:91]
	v_mfma_f32_16x16x32_bf16 v[80:83], v[140:143], v[230:233], v[80:83]
	v_mfma_f32_16x16x32_bf16 v[72:75], v[148:151], v[230:233], v[72:75]
	v_mfma_f32_16x16x32_bf16 v[60:63], v[140:143], v[238:241], v[60:63]
	v_mfma_f32_16x16x32_bf16 v[56:59], v[148:151], v[238:241], v[56:59]
	s_setprio 0
	s_setprio 1
	v_mfma_f32_16x16x32_bf16 v[36:39], v[152:155], v[210:213], v[36:39]
	v_mfma_f32_16x16x32_bf16 v[32:35], v[190:193], v[210:213], v[32:35]
	v_mfma_f32_16x16x32_bf16 v[28:31], v[152:155], v[218:221], v[28:31]
	v_mfma_f32_16x16x32_bf16 v[24:27], v[190:193], v[218:221], v[24:27]
	v_mfma_f32_16x16x32_bf16 v[20:23], v[152:155], v[226:229], v[20:23]
	v_mfma_f32_16x16x32_bf16 v[16:19], v[190:193], v[226:229], v[16:19]
	v_mfma_f32_16x16x32_bf16 v[12:15], v[152:155], v[234:237], v[12:15]
	v_mfma_f32_16x16x32_bf16 v[8:11], v[190:193], v[234:237], v[8:11]
	v_mfma_f32_16x16x32_bf16 v[36:39], v[186:189], v[214:217], v[36:39]
	v_mfma_f32_16x16x32_bf16 v[32:35], v[198:201], v[214:217], v[32:35]
	v_mfma_f32_16x16x32_bf16 v[28:31], v[186:189], v[222:225], v[28:31]
	v_mfma_f32_16x16x32_bf16 v[24:27], v[198:201], v[222:225], v[24:27]
	s_barrier
	v_mfma_f32_16x16x32_bf16 v[20:23], v[186:189], v[230:233], v[20:23]
	v_mfma_f32_16x16x32_bf16 v[16:19], v[198:201], v[230:233], v[16:19]
	v_mfma_f32_16x16x32_bf16 v[12:15], v[186:189], v[238:241], v[12:15]
	v_mfma_f32_16x16x32_bf16 v[8:11], v[198:201], v[238:241], v[8:11]
	s_setprio 0
	s_add_i32 s55, s55, 2
	s_add_u32 s8, s8, 0x100
	s_addc_u32 s9, s9, 0
	s_add_u32 s53, s53, 0x100
	s_addc_u32 s54, s54, 0
	s_cmp_gt_u32 s55, 13
	s_cbranch_scc0 .LBB0_165
	s_and_b64 vcc, exec, s[10:11]
	s_cbranch_vccz .LBB0_168
	s_barrier
	s_setprio 1

; #define PG8_STAGE(bufoff, gbase, voff) do { _Pragma("unroll") for (int _i = 0; _i < 2; ++_i) \
;         __builtin_amdgcn_global_load_lds((const unsigned*)((const char*)(gbase) + (voff)[_i]), (PG8_LAS unsigned*)(lds + (bufoff) + ldsw + _i * 8192), 16, 0, 0); } while (0)
; #define PG8_LDA(dst, b, h) do { _Pragma("unroll") for (int m = 0; m < 4; ++m) _Pragma("unroll") for (int k = 0; k < 2; ++k) dst[m][k] = *(const PG8_LAS bf16x8*)(lds + PG8_SA(b, h) + aoff + m * 2048 + k * 1024); } while (0)
; #define PG8_LDB(dst, b, h) do { _Pragma("unroll") for (int n = 0; n < 2; ++n) _Pragma("unroll") for (int k = 0; k < 2; ++k) dst[n][k] = *(const PG8_LAS bf16x8*)(lds + PG8_SB(b, h) + boff + n * 2048 + k * 1024); } while (0)
; #define PG8_MMA(ai, bj, At, Bt) do { __builtin_amdgcn_s_setprio(1); _Pragma("unroll") for (int m = 0; m < 4; ++m) _Pragma("unroll") for (int n = 0; n < 2; ++n) _Pragma("unroll") for (int k = 0; k < 2; ++k) \
;         acc[ai][bj][m][n] = __builtin_amdgcn_mfma_f32_16x16x32_bf16(Bt[n][k], At[m][k], acc[ai][bj][m][n], 0, 0, 0); __builtin_amdgcn_s_setprio(0); } while (0)
; #define PG8_WAIT_V(n) asm volatile("s_waitcnt vmcnt(" #n ")" ::: "memory")
; #define PG8_WAIT_L(n) asm volatile("s_waitcnt lgkmcnt(" #n ")" ::: "memory")
; #define PG8_BAR __builtin_amdgcn_s_barrier()
; #define PG8_SCHED __builtin_amdgcn_sched_barrier(0)
; template <class Epi, class Sched, bool ALIGN_EPI = false, bool SP2 = false>
; __device__ __forceinline__ void gemm_phase(PG8_LAS unsigned char* lds, const Gemm g, const Sched& S, const Epi& E) {
;     ...
;             PG8_LDB(B0, 0, 0); PG8_LDB(B1, 0, 1); PG8_SCHED; PG8_LDA(At, 0, 0); PG8_STAGE(PG8_SA(1, 1), a1 + hstep, voffA);
;             PG8_WAIT_V(8); PG8_WAIT_L(0); PG8_BAR; PG8_MMA(0, 0, At, B0); PG8_MMA(0, 1, At, B1); PG8_BAR; PG8_SCHED;
;             PG8_LDA(At, 0, 1); PG8_STAGE(PG8_SB(0, 0), b2, voffB); PG8_STAGE(PG8_SB(0, 1), b2 + hstep, voffB); PG8_STAGE(PG8_SA(0, 0), a2, voffA);
;             PG8_WAIT_V(8); PG8_WAIT_L(0); PG8_BAR; PG8_MMA(1, 0, At, B0); PG8_MMA(1, 1, At, B1); PG8_BAR; PG8_SCHED;
.LBB0_257:
	s_add_u32 s16, s8, 0xfffc0080
	s_addc_u32 s17, s9, -1
	s_add_i32 s18, 0, 0x10000
	s_cmp_eq_u32 s55, 12
	s_cselect_b32 s43, s14, s17
	s_cselect_b32 s42, s15, s16
	v_add_u32_e32 v0, s18, v210
	s_cselect_b32 s41, s13, s54
	s_cselect_b32 s40, s25, s53
	s_add_i32 s19, 0, 0x14000
	ds_read_b128 v[104:107], v0
	ds_read_b128 v[140:143], v0 offset:1024
	ds_read_b128 v[144:147], v0 offset:2048
	ds_read_b128 v[148:151], v0 offset:3072
	v_add_u32_e32 v0, s19, v210
	ds_read_b128 v[152:155], v0
	ds_read_b128 v[156:159], v0 offset:1024
	ds_read_b128 v[160:163], v0 offset:2048
	ds_read_b128 v[192:195], v0 offset:3072
	s_add_i32 m0, s44, 0xc000
	ds_read_b128 v[196:199], v212
	ds_read_b128 v[214:217], v212 offset:1024
	ds_read_b128 v[218:221], v212 offset:2048
	ds_read_b128 v[222:225], v212 offset:3072
	ds_read_b128 v[226:229], v212 offset:4096
	ds_read_b128 v[230:233], v212 offset:5120
	ds_read_b128 v[234:237], v212 offset:6144
	ds_read_b128 v[238:241], v212 offset:7168
	global_load_lds_dwordx4 v188, s[8:9]
	s_add_i32 m0, s44, 0xe000
	s_nop 0
	global_load_lds_dwordx4 v190, s[8:9]
	s_waitcnt vmcnt(8)
	s_waitcnt lgkmcnt(0)
	s_barrier
	s_waitcnt lgkmcnt(0)
	v_mfma_f32_16x16x32_bf16 v[136:139], v[104:107], v[196:199], v[136:139]
	v_mfma_f32_16x16x32_bf16 v[128:131], v[144:147], v[196:199], v[128:131]
	v_mfma_f32_16x16x32_bf16 v[120:123], v[104:107], v[218:221], v[120:123]
	v_mfma_f32_16x16x32_bf16 v[112:115], v[144:147], v[218:221], v[112:115]
	s_setprio 1
	v_mfma_f32_16x16x32_bf16 v[100:103], v[104:107], v[226:229], v[100:103]
	v_mfma_f32_16x16x32_bf16 v[92:95], v[144:147], v[226:229], v[92:95]
	v_mfma_f32_16x16x32_bf16 v[84:87], v[104:107], v[234:237], v[84:87]
	v_mfma_f32_16x16x32_bf16 v[76:79], v[144:147], v[234:237], v[76:79]
	v_mfma_f32_16x16x32_bf16 v[136:139], v[140:143], v[214:217], v[136:139]
	v_mfma_f32_16x16x32_bf16 v[128:131], v[148:151], v[214:217], v[128:131]
	v_mfma_f32_16x16x32_bf16 v[120:123], v[140:143], v[222:225], v[120:123]
	v_mfma_f32_16x16x32_bf16 v[112:115], v[148:151], v[222:225], v[112:115]
	v_mfma_f32_16x16x32_bf16 v[100:103], v[140:143], v[230:233], v[100:103]
	v_mfma_f32_16x16x32_bf16 v[92:95], v[148:151], v[230:233], v[92:95]
	v_mfma_f32_16x16x32_bf16 v[84:87], v[140:143], v[238:241], v[84:87]
	v_mfma_f32_16x16x32_bf16 v[76:79], v[148:151], v[238:241], v[76:79]
	s_setprio 0
	s_setprio 1
	v_mfma_f32_16x16x32_bf16 v[132:135], v[152:155], v[196:199], v[132:135]
	v_mfma_f32_16x16x32_bf16 v[124:127], v[160:163], v[196:199], v[124:127]
	v_mfma_f32_16x16x32_bf16 v[116:119], v[152:155], v[218:221], v[116:119]
	v_mfma_f32_16x16x32_bf16 v[108:111], v[160:163], v[218:221], v[108:111]
	v_mfma_f32_16x16x32_bf16 v[96:99], v[152:155], v[226:229], v[96:99]
	v_mfma_f32_16x16x32_bf16 v[88:91], v[160:163], v[226:229], v[88:91]
	v_mfma_f32_16x16x32_bf16 v[80:83], v[152:155], v[234:237], v[80:83]
	v_mfma_f32_16x16x32_bf16 v[72:75], v[160:163], v[234:237], v[72:75]
	v_mfma_f32_16x16x32_bf16 v[132:135], v[156:159], v[214:217], v[132:135]
	v_mfma_f32_16x16x32_bf16 v[124:127], v[192:195], v[214:217], v[124:127]
	v_mfma_f32_16x16x32_bf16 v[116:119], v[156:159], v[222:225], v[116:119]
	v_mfma_f32_16x16x32_bf16 v[108:111], v[192:195], v[222:225], v[108:111]
	s_barrier
	v_mfma_f32_16x16x32_bf16 v[96:99], v[156:159], v[230:233], v[96:99]
	v_mfma_f32_16x16x32_bf16 v[88:91], v[192:195], v[230:233], v[88:91]
	v_mfma_f32_16x16x32_bf16 v[80:83], v[156:159], v[238:241], v[80:83]
	v_mfma_f32_16x16x32_bf16 v[72:75], v[192:195], v[238:241], v[72:75]
	s_setprio 0
	s_add_i32 s16, s18, s36
	s_mov_b32 m0, s16
	ds_read_b128 v[196:199], v212 offset:16384
	ds_read_b128 v[214:217], v212 offset:17408
	ds_read_b128 v[218:221], v212 offset:18432
	ds_read_b128 v[222:225], v212 offset:19456
	ds_read_b128 v[226:229], v212 offset:20480
	ds_read_b128 v[230:233], v212 offset:21504
	ds_read_b128 v[234:237], v212 offset:22528
	ds_read_b128 v[238:241], v212 offset:23552
	global_load_lds_dwordx4 v182, s[40:41]
	s_add_i32 m0, s16, 0x2000
	s_add_u32 s16, s40, 0x40000
	s_addc_u32 s17, s41, 0
	s_add_i32 s18, s19, s36
	global_load_lds_dwordx4 v178, s[40:41]
	s_mov_b32 m0, s18
	s_nop 0
	global_load_lds_dwordx4 v182, s[16:17]
	s_add_i32 m0, s18, 0x2000
	s_nop 0
	global_load_lds_dwordx4 v178, s[16:17]
	s_mov_b32 m0, s44
	s_nop 0
	global_load_lds_dwordx4 v184, s[42:43]
	s_mov_b32 m0, s45
	s_nop 0
	global_load_lds_dwordx4 v180, s[42:43]
	s_waitcnt vmcnt(8)
	s_waitcnt lgkmcnt(0)
	s_barrier
	s_waitcnt lgkmcnt(0)
	v_mfma_f32_16x16x32_bf16 v[68:71], v[104:107], v[196:199], v[68:71]
	v_mfma_f32_16x16x32_bf16 v[60:63], v[144:147], v[196:199], v[60:63]
	v_mfma_f32_16x16x32_bf16 v[52:55], v[104:107], v[218:221], v[52:55]
	v_mfma_f32_16x16x32_bf16 v[44:47], v[144:147], v[218:221], v[44:47]
	s_setprio 1
	v_mfma_f32_16x16x32_bf16 v[36:39], v[104:107], v[226:229], v[36:39]
	v_mfma_f32_16x16x32_bf16 v[28:31], v[144:147], v[226:229], v[28:31]
	v_mfma_f32_16x16x32_bf16 v[20:23], v[104:107], v[234:237], v[20:23]
	v_mfma_f32_16x16x32_bf16 v[12:15], v[144:147], v[234:237], v[12:15]
	v_mfma_f32_16x16x32_bf16 v[68:71], v[140:143], v[214:217], v[68:71]
	v_mfma_f32_16x16x32_bf16 v[60:63], v[148:151], v[214:217], v[60:63]
	v_mfma_f32_16x16x32_bf16 v[52:55], v[140:143], v[222:225], v[52:55]
	v_mfma_f32_16x16x32_bf16 v[44:47], v[148:151], v[222:225], v[44:47]
	v_mfma_f32_16x16x32_bf16 v[36:39], v[140:143], v[230:233], v[36:39]
	v_mfma_f32_16x16x32_bf16 v[28:31], v[148:151], v[230:233], v[28:31]
	v_mfma_f32_16x16x32_bf16 v[20:23], v[140:143], v[238:241], v[20:23]
	v_mfma_f32_16x16x32_bf16 v[12:15], v[148:151], v[238:241], v[12:15]
	s_setprio 0
	s_setprio 1
	v_mfma_f32_16x16x32_bf16 v[64:67], v[152:155], v[196:199], v[64:67]
	v_mfma_f32_16x16x32_bf16 v[56:59], v[160:163], v[196:199], v[56:59]
	v_mfma_f32_16x16x32_bf16 v[48:51], v[152:155], v[218:221], v[48:51]
	v_mfma_f32_16x16x32_bf16 v[40:43], v[160:163], v[218:221], v[40:43]
	v_mfma_f32_16x16x32_bf16 v[32:35], v[152:155], v[226:229], v[32:35]
	v_mfma_f32_16x16x32_bf16 v[24:27], v[160:163], v[226:229], v[24:27]
	v_mfma_f32_16x16x32_bf16 v[16:19], v[152:155], v[234:237], v[16:19]
	v_mfma_f32_16x16x32_bf16 v[8:11], v[160:163], v[234:237], v[8:11]
	v_mfma_f32_16x16x32_bf16 v[64:67], v[156:159], v[214:217], v[64:67]
	v_mfma_f32_16x16x32_bf16 v[56:59], v[192:195], v[214:217], v[56:59]
	v_mfma_f32_16x16x32_bf16 v[48:51], v[156:159], v[222:225], v[48:51]
	v_mfma_f32_16x16x32_bf16 v[40:43], v[192:195], v[222:225], v[40:43]
	s_barrier
; #define PG8_STAGE(bufoff, gbase, voff) do { _Pragma("unroll") for (int _i = 0; _i < 2; ++_i) \
;         __builtin_amdgcn_global_load_lds((const unsigned*)((const char*)(gbase) + (voff)[_i]), (PG8_LAS unsigned*)(lds + (bufoff) + ldsw + _i * 8192), 16, 0, 0); } while (0)
; #define PG8_LDA(dst, b, h) do { _Pragma("unroll") for (int m = 0; m < 4; ++m) _Pragma("unroll") for (int k = 0; k < 2; ++k) dst[m][k] = *(const PG8_LAS bf16x8*)(lds + PG8_SA(b, h) + aoff + m * 2048 + k * 1024); } while (0)
; #define PG8_LDB(dst, b, h) do { _Pragma("unroll") for (int n = 0; n < 2; ++n) _Pragma("unroll") for (int k = 0; k < 2; ++k) dst[n][k] = *(const PG8_LAS bf16x8*)(lds + PG8_SB(b, h) + boff + n * 2048 + k * 1024); } while (0)
; #define PG8_MMA(ai, bj, At, Bt) do { __builtin_amdgcn_s_setprio(1); _Pragma("unroll") for (int m = 0; m < 4; ++m) _Pragma("unroll") for (int n = 0; n < 2; ++n) _Pragma("unroll") for (int k = 0; k < 2; ++k) \
;         acc[ai][bj][m][n] = __builtin_amdgcn_mfma_f32_16x16x32_bf16(Bt[n][k], At[m][k], acc[ai][bj][m][n], 0, 0, 0); __builtin_amdgcn_s_setprio(0); } while (0)
; #define PG8_WAIT_V(n) asm volatile("s_waitcnt vmcnt(" #n ")" ::: "memory")
; #define PG8_WAIT_L(n) asm volatile("s_waitcnt lgkmcnt(" #n ")" ::: "memory")
; #define PG8_BAR __builtin_amdgcn_s_barrier()
; #define PG8_SCHED __builtin_amdgcn_sched_barrier(0)
; template <class Epi, class Sched, bool ALIGN_EPI = false, bool SP2 = false>
; __device__ __forceinline__ void gemm_phase(PG8_LAS unsigned char* lds, const Gemm g, const Sched& S, const Epi& E) {
;     ...
;             PG8_LDB(B0, 1, 0); PG8_LDB(B1, 1, 1); PG8_SCHED; PG8_LDA(At, 1, 0); PG8_STAGE(PG8_SA(0, 1), a2 + hstep, voffA);
;             PG8_WAIT_V(8); PG8_WAIT_L(0); PG8_BAR; PG8_MMA(0, 0, At, B0); PG8_MMA(0, 1, At, B1); PG8_BAR; PG8_SCHED;
	v_mfma_f32_16x16x32_bf16 v[32:35], v[156:159], v[230:233], v[32:35]
	v_mfma_f32_16x16x32_bf16 v[24:27], v[192:195], v[230:233], v[24:27]
	v_mfma_f32_16x16x32_bf16 v[16:19], v[156:159], v[238:241], v[16:19]
	v_mfma_f32_16x16x32_bf16 v[8:11], v[192:195], v[238:241], v[8:11]
	s_setprio 0
	s_add_i32 s18, 0, 0x18000
	v_add_u32_e32 v0, s18, v210
	ds_read_b128 v[104:107], v0
	ds_read_b128 v[140:143], v0 offset:1024
	ds_read_b128 v[144:147], v0 offset:2048
	ds_read_b128 v[148:151], v0 offset:3072
	v_add_u32_e32 v0, s33, v210
	ds_read_b128 v[152:155], v0
	ds_read_b128 v[156:159], v0 offset:1024
	ds_read_b128 v[160:163], v0 offset:2048
	ds_read_b128 v[192:195], v0 offset:3072
	s_add_u32 s16, s42, 0x40000
	s_addc_u32 s17, s43, 0
	s_mov_b32 m0, s46
	ds_read_b128 v[196:199], v212 offset:32768
	ds_read_b128 v[214:217], v212 offset:33792
	ds_read_b128 v[218:221], v212 offset:34816
	ds_read_b128 v[222:225], v212 offset:35840
	ds_read_b128 v[226:229], v212 offset:36864
	ds_read_b128 v[230:233], v212 offset:37888
	ds_read_b128 v[234:237], v212 offset:38912
	ds_read_b128 v[238:241], v212 offset:39936
	global_load_lds_dwordx4 v184, s[16:17]
	s_mov_b32 m0, s47
	s_nop 0
	global_load_lds_dwordx4 v180, s[16:17]
	s_waitcnt vmcnt(8)
	s_waitcnt lgkmcnt(0)
	s_barrier
	s_waitcnt lgkmcnt(0)
	v_mfma_f32_16x16x32_bf16 v[136:139], v[104:107], v[196:199], v[136:139]
	v_mfma_f32_16x16x32_bf16 v[128:131], v[144:147], v[196:199], v[128:131]
	v_mfma_f32_16x16x32_bf16 v[120:123], v[104:107], v[218:221], v[120:123]
	v_mfma_f32_16x16x32_bf16 v[112:115], v[144:147], v[218:221], v[112:115]
	s_setprio 1
	v_mfma_f32_16x16x32_bf16 v[100:103], v[104:107], v[226:229], v[100:103]
	v_mfma_f32_16x16x32_bf16 v[92:95], v[144:147], v[226:229], v[92:95]
	v_mfma_f32_16x16x32_bf16 v[84:87], v[104:107], v[234:237], v[84:87]
	v_mfma_f32_16x16x32_bf16 v[76:79], v[144:147], v[234:237], v[76:79]
	v_mfma_f32_16x16x32_bf16 v[136:139], v[140:143], v[214:217], v[136:139]
	v_mfma_f32_16x16x32_bf16 v[128:131], v[148:151], v[214:217], v[128:131]
	v_mfma_f32_16x16x32_bf16 v[120:123], v[140:143], v[222:225], v[120:123]
	v_mfma_f32_16x16x32_bf16 v[112:115], v[148:151], v[222:225], v[112:115]
	v_mfma_f32_16x16x32_bf16 v[100:103], v[140:143], v[230:233], v[100:103]
	v_mfma_f32_16x16x32_bf16 v[92:95], v[148:151], v[230:233], v[92:95]
	v_mfma_f32_16x16x32_bf16 v[84:87], v[140:143], v[238:241], v[84:87]
	v_mfma_f32_16x16x32_bf16 v[76:79], v[148:151], v[238:241], v[76:79]
	s_setprio 0
	s_setprio 1
	v_mfma_f32_16x16x32_bf16 v[132:135], v[152:155], v[196:199], v[132:135]
	v_mfma_f32_16x16x32_bf16 v[124:127], v[160:163], v[196:199], v[124:127]
	v_mfma_f32_16x16x32_bf16 v[116:119], v[152:155], v[218:221], v[116:119]
	v_mfma_f32_16x16x32_bf16 v[108:111], v[160:163], v[218:221], v[108:111]
	v_mfma_f32_16x16x32_bf16 v[96:99], v[152:155], v[226:229], v[96:99]
	v_mfma_f32_16x16x32_bf16 v[88:91], v[160:163], v[226:229], v[88:91]
	v_mfma_f32_16x16x32_bf16 v[80:83], v[152:155], v[234:237], v[80:83]
	v_mfma_f32_16x16x32_bf16 v[72:75], v[160:163], v[234:237], v[72:75]
	v_mfma_f32_16x16x32_bf16 v[132:135], v[156:159], v[214:217], v[132:135]
	v_mfma_f32_16x16x32_bf16 v[124:127], v[192:195], v[214:217], v[124:127]
	v_mfma_f32_16x16x32_bf16 v[116:119], v[156:159], v[222:225], v[116:119]
	v_mfma_f32_16x16x32_bf16 v[108:111], v[192:195], v[222:225], v[108:111]
	s_barrier
; #define PG8_STAGE(bufoff, gbase, voff) do { _Pragma("unroll") for (int _i = 0; _i < 2; ++_i) \
;         __builtin_amdgcn_global_load_lds((const unsigned*)((const char*)(gbase) + (voff)[_i]), (PG8_LAS unsigned*)(lds + (bufoff) + ldsw + _i * 8192), 16, 0, 0); } while (0)
; #define PG8_LDA(dst, b, h) do { _Pragma("unroll") for (int m = 0; m < 4; ++m) _Pragma("unroll") for (int k = 0; k < 2; ++k) dst[m][k] = *(const PG8_LAS bf16x8*)(lds + PG8_SA(b, h) + aoff + m * 2048 + k * 1024); } while (0)
; #define PG8_MMA(ai, bj, At, Bt) do { __builtin_amdgcn_s_setprio(1); _Pragma("unroll") for (int m = 0; m < 4; ++m) _Pragma("unroll") for (int n = 0; n < 2; ++n) _Pragma("unroll") for (int k = 0; k < 2; ++k) \
;         acc[ai][bj][m][n] = __builtin_amdgcn_mfma_f32_16x16x32_bf16(Bt[n][k], At[m][k], acc[ai][bj][m][n], 0, 0, 0); __builtin_amdgcn_s_setprio(0); } while (0)
; #define PG8_WAIT_V(n) asm volatile("s_waitcnt vmcnt(" #n ")" ::: "memory")
; #define PG8_WAIT_L(n) asm volatile("s_waitcnt lgkmcnt(" #n ")" ::: "memory")
; #define PG8_BAR __builtin_amdgcn_s_barrier()
; #define PG8_SCHED __builtin_amdgcn_sched_barrier(0)
; template <class Epi, class Sched, bool ALIGN_EPI = false, bool SP2 = false>
; __device__ __forceinline__ void gemm_phase(PG8_LAS unsigned char* lds, const Gemm g, const Sched& S, const Epi& E) {
;     ...
;         for (int t = 0; t < nt; t += 2) {
;             const bool last = (t == nt - 2);
;             const char* a1 = cA + (size_t)(t + 1) * kstep;
;             const char* a2 = last ? nA : cA + (size_t)(t + 2) * kstep; const char* b2 = last ? nB : cB + (size_t)(t + 2) * kstep;
;             const char* a3 = a2 + kstep; const char* b3 = b2 + kstep;
;     ...
;             PG8_LDA(At, 1, 1); PG8_STAGE(PG8_SB(1, 0), b3, voffB); PG8_STAGE(PG8_SB(1, 1), b3 + hstep, voffB); PG8_STAGE(PG8_SA(1, 0), a3, voffA);
;             PG8_WAIT_V(8); PG8_WAIT_L(0); PG8_BAR; PG8_MMA(1, 0, At, B0); PG8_MMA(1, 1, At, B1); PG8_BAR; PG8_SCHED;
	v_mfma_f32_16x16x32_bf16 v[96:99], v[156:159], v[230:233], v[96:99]
	v_mfma_f32_16x16x32_bf16 v[88:91], v[192:195], v[230:233], v[88:91]
	v_mfma_f32_16x16x32_bf16 v[80:83], v[156:159], v[238:241], v[80:83]
	v_mfma_f32_16x16x32_bf16 v[72:75], v[192:195], v[238:241], v[72:75]
	s_setprio 0
	s_add_i32 m0, s18, s36
	s_add_u32 s16, s40, 0x80
	s_addc_u32 s17, s41, 0
	ds_read_b128 v[196:199], v212 offset:49152
	ds_read_b128 v[214:217], v212 offset:50176
	ds_read_b128 v[218:221], v212 offset:51200
	ds_read_b128 v[222:225], v212 offset:52224
	ds_read_b128 v[226:229], v212 offset:53248
	ds_read_b128 v[230:233], v212 offset:54272
	ds_read_b128 v[234:237], v212 offset:55296
	ds_read_b128 v[238:241], v212 offset:56320
	global_load_lds_dwordx4 v182, s[16:17]
	s_add_i32 m0, m0, 0x2000
	s_nop 0
	global_load_lds_dwordx4 v178, s[16:17]
	s_add_u32 s16, s40, 0x40080
	s_addc_u32 s17, s41, 0
	s_add_i32 m0, s33, s36
	s_nop 0
	global_load_lds_dwordx4 v182, s[16:17]
	s_add_i32 m0, m0, 0x2000
	s_nop 0
	global_load_lds_dwordx4 v178, s[16:17]
	s_add_u32 s16, s42, 0x80
	s_addc_u32 s17, s43, 0
	s_mov_b32 m0, s48
	s_nop 0
	global_load_lds_dwordx4 v184, s[16:17]
	s_mov_b32 m0, s49
	s_nop 0
	global_load_lds_dwordx4 v180, s[16:17]
	s_waitcnt vmcnt(8)
	s_waitcnt lgkmcnt(0)
	s_barrier
	s_waitcnt lgkmcnt(0)
	v_mfma_f32_16x16x32_bf16 v[68:71], v[104:107], v[196:199], v[68:71]
	v_mfma_f32_16x16x32_bf16 v[60:63], v[144:147], v[196:199], v[60:63]
	v_mfma_f32_16x16x32_bf16 v[52:55], v[104:107], v[218:221], v[52:55]
	v_mfma_f32_16x16x32_bf16 v[44:47], v[144:147], v[218:221], v[44:47]
	s_setprio 1
	v_mfma_f32_16x16x32_bf16 v[36:39], v[104:107], v[226:229], v[36:39]
	v_mfma_f32_16x16x32_bf16 v[28:31], v[144:147], v[226:229], v[28:31]
	v_mfma_f32_16x16x32_bf16 v[20:23], v[104:107], v[234:237], v[20:23]
	v_mfma_f32_16x16x32_bf16 v[12:15], v[144:147], v[234:237], v[12:15]
	v_mfma_f32_16x16x32_bf16 v[68:71], v[140:143], v[214:217], v[68:71]
	v_mfma_f32_16x16x32_bf16 v[60:63], v[148:151], v[214:217], v[60:63]
	v_mfma_f32_16x16x32_bf16 v[52:55], v[140:143], v[222:225], v[52:55]
	v_mfma_f32_16x16x32_bf16 v[44:47], v[148:151], v[222:225], v[44:47]
	v_mfma_f32_16x16x32_bf16 v[36:39], v[140:143], v[230:233], v[36:39]
	v_mfma_f32_16x16x32_bf16 v[28:31], v[148:151], v[230:233], v[28:31]
	v_mfma_f32_16x16x32_bf16 v[20:23], v[140:143], v[238:241], v[20:23]
	v_mfma_f32_16x16x32_bf16 v[12:15], v[148:151], v[238:241], v[12:15]
	s_setprio 0
	s_setprio 1
	v_mfma_f32_16x16x32_bf16 v[64:67], v[152:155], v[196:199], v[64:67]
	v_mfma_f32_16x16x32_bf16 v[56:59], v[160:163], v[196:199], v[56:59]
	v_mfma_f32_16x16x32_bf16 v[48:51], v[152:155], v[218:221], v[48:51]
	v_mfma_f32_16x16x32_bf16 v[40:43], v[160:163], v[218:221], v[40:43]
	v_mfma_f32_16x16x32_bf16 v[32:35], v[152:155], v[226:229], v[32:35]
	v_mfma_f32_16x16x32_bf16 v[24:27], v[160:163], v[226:229], v[24:27]
	v_mfma_f32_16x16x32_bf16 v[16:19], v[152:155], v[234:237], v[16:19]
	v_mfma_f32_16x16x32_bf16 v[8:11], v[160:163], v[234:237], v[8:11]
	v_mfma_f32_16x16x32_bf16 v[64:67], v[156:159], v[214:217], v[64:67]
	v_mfma_f32_16x16x32_bf16 v[56:59], v[192:195], v[214:217], v[56:59]
	v_mfma_f32_16x16x32_bf16 v[48:51], v[156:159], v[222:225], v[48:51]
	v_mfma_f32_16x16x32_bf16 v[40:43], v[192:195], v[222:225], v[40:43]
	s_barrier
	v_mfma_f32_16x16x32_bf16 v[32:35], v[156:159], v[230:233], v[32:35]
	v_mfma_f32_16x16x32_bf16 v[24:27], v[192:195], v[230:233], v[24:27]
	v_mfma_f32_16x16x32_bf16 v[16:19], v[156:159], v[238:241], v[16:19]
	v_mfma_f32_16x16x32_bf16 v[8:11], v[192:195], v[238:241], v[8:11]
	s_setprio 0
	s_add_i32 s55, s55, 2
	s_add_u32 s8, s8, 0x100
	s_addc_u32 s9, s9, 0
	s_add_u32 s53, s53, 0x100
	s_addc_u32 s54, s54, 0
	s_cmp_gt_u32 s55, 13
	s_cbranch_scc0 .LBB0_257
	s_and_b64 vcc, exec, s[10:11]
	s_cbranch_vccz .LBB0_260
	s_barrier
	s_setprio 1
